# hg_sequence: 24-bit integer multiplies (v_mul_u32_u24 / v_mad_u32_u24) replace quarter-rate v_mul_lo_u32 and v_mad_u64_u32 in LDS address math
# speedup vs baseline: 1.0018x; 1.0018x over previous
.LBB0_1409:
	v_add_u32_e32 v0, s82, v67
	v_bfe_u32 v62, v58, 16, 1
	s_movk_i32 s26, 0x7fff
	v_add3_u32 v58, v58, v62, s26
	v_mad_u32_u24 v62, v0, s73, v66
	v_bfe_u32 v0, v59, 16, 1
	v_add3_u32 v0, v59, v0, s26
	ds_write_b16_d16_hi v62, v0 offset:144
	v_bfe_u32 v0, v60, 16, 1
	v_add3_u32 v0, v60, v0, s26
	ds_write_b16_d16_hi v62, v0 offset:288
	v_bfe_u32 v0, v61, 16, 1
	v_add3_u32 v0, v61, v0, s26
	ds_write_b16_d16_hi v62, v0 offset:432
	v_add_u32_e32 v0, s56, v99
	v_mul_u32_u24_e32 v0, s73, v0
	s_add_i32 s2, 0, 0x15200
	v_lshlrev_b32_e32 v94, 4, v100
	v_add3_u32 v0, s2, v0, v94
	s_add_i32 s2, 0, 0x1e200
	v_add_u32_e32 v95, s2, v94
	s_movk_i32 s2, 0x110
	v_lshlrev_b32_e32 v86, 3, v100
	v_mul_u32_u24_e32 v87, s2, v99
	v_add3_u32 v97, 0, v86, v87
	ds_write_b16_d16_hi v62, v58
	v_add_u32_e32 v96, 0x6000, v97
	v_pk_add_f32 v[84:85], v[84:85], v[64:65]
	s_waitcnt lgkmcnt(0)
	s_barrier
	v_cvt_pk_bf16_f32 v78, v50, v51
	v_cvt_pk_bf16_f32 v79, v52, v53
	v_cvt_pk_bf16_f32 v80, v54, v55
	v_cvt_pk_bf16_f32 v81, v56, v57
	v_cvt_pk_bf16_f32 v74, v42, v43
	v_cvt_pk_bf16_f32 v75, v44, v45
	v_cvt_pk_bf16_f32 v76, v46, v47
	v_cvt_pk_bf16_f32 v77, v48, v49
	v_cvt_pk_bf16_f32 v70, v30, v31
	v_cvt_pk_bf16_f32 v71, v32, v33
	v_cvt_pk_bf16_f32 v72, v38, v39
	v_cvt_pk_bf16_f32 v73, v40, v41
	v_cvt_pk_bf16_f32 v66, v26, v27
	v_cvt_pk_bf16_f32 v67, v28, v29
	v_cvt_pk_bf16_f32 v68, v34, v35
	v_cvt_pk_bf16_f32 v69, v36, v37
	ds_read_b128 v[62:65], v0
	ds_read_b128 v[58:61], v0 offset:64
	ds_read2_b64 v[128:131], v96 offset0:128 offset1:132
	ds_read2_b64 v[132:135], v96 offset0:136 offset1:140
	ds_read2_b64 v[136:139], v96 offset0:144 offset1:148
	ds_read2_b64 v[140:143], v96 offset0:152 offset1:156
	v_lshl_add_u32 v0, v100, 12, v99
	v_mul_u32_u24_e32 v96, s73, v99
	v_add_u32_e32 v108, 0x7000, v97
	v_add_u32_e32 v127, v95, v96
	ds_read_b128 v[144:147], v127
	ds_read_b128 v[148:151], v127 offset:64
	ds_read2_b64 v[152:155], v108 offset0:160 offset1:164
	ds_read2_b64 v[156:159], v108 offset0:168 offset1:172
	ds_read2_b64 v[160:163], v108 offset0:176 offset1:180
	ds_read2_b64 v[164:167], v108 offset0:184 offset1:188
	ds_read_b128 v[168:171], v127 offset:2304
	ds_read_b128 v[172:175], v127 offset:2368
	s_waitcnt lgkmcnt(11)
	v_mfma_f32_16x16x32_bf16 v[86:89], v[128:131], v[78:81], 0
	s_waitcnt lgkmcnt(10)
	v_mfma_f32_16x16x32_bf16 v[86:89], v[132:135], v[74:77], v[86:89]
	s_waitcnt lgkmcnt(9)
	v_mfma_f32_16x16x32_bf16 v[86:89], v[136:139], v[70:73], v[86:89]
	s_waitcnt lgkmcnt(8)
	v_mfma_f32_16x16x32_bf16 v[86:89], v[140:143], v[66:69], v[86:89]
	s_waitcnt lgkmcnt(7)
	v_mfma_f32_16x16x32_bf16 v[86:89], v[144:147], v[62:65], v[86:89]
	s_waitcnt lgkmcnt(6)
	v_mfma_f32_16x16x32_bf16 v[100:103], v[148:151], v[58:61], v[86:89]
	v_add_u32_e32 v99, 0x8000, v97
	ds_read2_b64 v[128:131], v99 offset0:192 offset1:196
	ds_read2_b64 v[132:135], v99 offset0:200 offset1:204
	ds_read2_b64 v[136:139], v99 offset0:208 offset1:212
	ds_read2_b64 v[140:143], v99 offset0:216 offset1:220
	ds_read_b128 v[144:147], v127 offset:4608
	ds_read_b128 v[148:151], v127 offset:4672
	v_lshlrev_b32_e32 v86, 2, v0
	s_add_u32 s2, s74, 0xfffd0000
	s_addc_u32 s3, s75, -1
	v_add_u32_e32 v86, 0x1000, v86
	v_add_u32_e32 v87, 0x2000, v86
	global_store_dword v86, v100, s[2:3] offset:-4096
	global_store_dword v86, v101, s[2:3]
	global_store_dword v87, v102, s[2:3] offset:-4096
	global_store_dword v87, v103, s[2:3]
	s_waitcnt lgkmcnt(11)
	v_mfma_f32_16x16x32_bf16 v[100:103], v[152:155], v[78:81], 0
	s_waitcnt lgkmcnt(10)
	v_mfma_f32_16x16x32_bf16 v[100:103], v[156:159], v[74:77], v[100:103]
	s_waitcnt lgkmcnt(9)
	v_mfma_f32_16x16x32_bf16 v[100:103], v[160:163], v[70:73], v[100:103]
	s_waitcnt lgkmcnt(8)
	v_mfma_f32_16x16x32_bf16 v[100:103], v[164:167], v[66:69], v[100:103]
	s_waitcnt lgkmcnt(7)
	v_mfma_f32_16x16x32_bf16 v[100:103], v[168:171], v[62:65], v[100:103]
	s_waitcnt lgkmcnt(6)
	v_mfma_f32_16x16x32_bf16 v[100:103], v[172:175], v[58:61], v[100:103]
	v_add_u32_e32 v97, 0x9000, v97
	ds_read2_b64 v[152:155], v97 offset0:224 offset1:228
	ds_read2_b64 v[156:159], v97 offset0:232 offset1:236
	ds_read2_b64 v[160:163], v97 offset0:240 offset1:244
	ds_read2_b64 v[164:167], v97 offset0:248 offset1:252
	ds_read_b128 v[168:171], v127 offset:6912
	ds_read_b128 v[172:175], v127 offset:6976
	s_add_u32 s2, s74, 0xfffe0000
	s_addc_u32 s3, s75, -1
	global_store_dword v86, v100, s[2:3] offset:-4096
	global_store_dword v86, v101, s[2:3]
	global_store_dword v87, v102, s[2:3] offset:-4096
	global_store_dword v87, v103, s[2:3]
	s_waitcnt lgkmcnt(11)
	v_mfma_f32_16x16x32_bf16 v[100:103], v[128:131], v[78:81], 0
	s_waitcnt lgkmcnt(10)
	v_mfma_f32_16x16x32_bf16 v[100:103], v[132:135], v[74:77], v[100:103]
	s_waitcnt lgkmcnt(9)
	v_mfma_f32_16x16x32_bf16 v[100:103], v[136:139], v[70:73], v[100:103]
	s_waitcnt lgkmcnt(8)
	v_mfma_f32_16x16x32_bf16 v[100:103], v[140:143], v[66:69], v[100:103]
	s_waitcnt lgkmcnt(7)
	v_mfma_f32_16x16x32_bf16 v[100:103], v[144:147], v[62:65], v[100:103]
	s_waitcnt lgkmcnt(6)
	v_mfma_f32_16x16x32_bf16 v[100:103], v[148:151], v[58:61], v[100:103]
	v_add_u32_e32 v127, 0x19a00, v94
	v_add_u32_e32 v127, v127, v96
	ds_read_b128 v[128:131], v94 offset:6144
	ds_read_b128 v[132:135], v127
	ds_read_b128 v[136:139], v127 offset:64
	ds_read_b128 v[140:143], v94 offset:6208
	ds_read_b128 v[144:147], v127 offset:2304
	ds_read_b128 v[148:151], v127 offset:2368
	s_add_u32 s2, s74, 0xffff0000
	s_addc_u32 s3, s75, -1
	global_store_dword v86, v100, s[2:3] offset:-4096
	global_store_dword v86, v101, s[2:3]
	global_store_dword v87, v102, s[2:3] offset:-4096
	global_store_dword v87, v103, s[2:3]
	s_waitcnt lgkmcnt(11)
	v_mfma_f32_16x16x32_bf16 v[78:81], v[152:155], v[78:81], 0
	s_waitcnt lgkmcnt(10)
	v_mfma_f32_16x16x32_bf16 v[74:77], v[156:159], v[74:77], v[78:81]
	s_waitcnt lgkmcnt(9)
	v_mfma_f32_16x16x32_bf16 v[70:73], v[160:163], v[70:73], v[74:77]
	s_waitcnt lgkmcnt(8)
	v_mfma_f32_16x16x32_bf16 v[66:69], v[164:167], v[66:69], v[70:73]
	s_waitcnt lgkmcnt(7)
	v_mfma_f32_16x16x32_bf16 v[66:69], v[168:171], v[62:65], v[66:69]
	s_waitcnt lgkmcnt(6)
	v_mfma_f32_16x16x32_bf16 v[66:69], v[172:175], v[58:61], v[66:69]
	ds_read_b128 v[152:155], v94 offset:6272
	ds_read_b128 v[156:159], v127 offset:4608
	ds_read_b128 v[160:163], v127 offset:4672
	ds_read_b128 v[164:167], v94 offset:6336
	ds_read_b128 v[168:171], v127 offset:6912
	ds_read_b128 v[172:175], v127 offset:6976
	s_nop 1
	global_store_dword v86, v66, s[74:75] offset:-4096
	global_store_dword v86, v67, s[74:75]
	global_store_dword v87, v68, s[74:75] offset:-4096
	global_store_dword v87, v69, s[74:75]
	s_add_u32 s34, s34, 0x20000
	s_addc_u32 s35, s35, 0
	s_add_u32 s74, s74, 0x40000
	s_addc_u32 s75, s75, 0
	s_mov_b32 s2, 0x19a00
	s_cmp_eq_u32 s34, 0x400000
	s_waitcnt lgkmcnt(11)
	v_pk_mul_f32 v[50:51], v[50:51], v[128:129]
	v_pk_mul_f32 v[52:53], v[52:53], v[130:131]
	s_waitcnt lgkmcnt(10)
	s_nop 0
	v_mfma_f32_16x16x32_bf16 v[50:53], v[132:135], v[62:65], v[50:53]
	s_waitcnt lgkmcnt(9)
	v_mfma_f32_16x16x32_bf16 v[50:53], v[136:139], v[58:61], v[50:53]
	ds_read_b128 v[128:131], v94 offset:6400
	ds_read_b128 v[132:135], v127 offset:9216
	ds_read_b128 v[136:139], v127 offset:9280
	s_waitcnt lgkmcnt(11)
	v_pk_mul_f32 v[54:55], v[54:55], v[140:141]
	v_pk_mul_f32 v[56:57], v[56:57], v[142:143]
	s_waitcnt lgkmcnt(10)
	s_nop 0
	v_mfma_f32_16x16x32_bf16 v[54:57], v[144:147], v[62:65], v[54:57]
	s_waitcnt lgkmcnt(9)
	v_mfma_f32_16x16x32_bf16 v[54:57], v[148:151], v[58:61], v[54:57]
	ds_read_b128 v[140:143], v94 offset:6464
	ds_read_b128 v[144:147], v127 offset:11520
	ds_read_b128 v[148:151], v127 offset:11584
	s_waitcnt lgkmcnt(11)
	v_pk_mul_f32 v[42:43], v[42:43], v[152:153]
	v_pk_mul_f32 v[44:45], v[44:45], v[154:155]
	s_waitcnt lgkmcnt(10)
	s_nop 0
	v_mfma_f32_16x16x32_bf16 v[42:45], v[156:159], v[62:65], v[42:45]
	s_waitcnt lgkmcnt(9)
	v_mfma_f32_16x16x32_bf16 v[42:45], v[160:163], v[58:61], v[42:45]
	ds_read_b128 v[152:155], v94 offset:6528
	ds_read_b128 v[156:159], v127 offset:13824
	ds_read_b128 v[160:163], v127 offset:13888
	s_waitcnt lgkmcnt(11)
	v_pk_mul_f32 v[46:47], v[46:47], v[164:165]
	v_pk_mul_f32 v[48:49], v[48:49], v[166:167]
	s_waitcnt lgkmcnt(10)
	s_nop 0
	v_mfma_f32_16x16x32_bf16 v[46:49], v[168:171], v[62:65], v[46:49]
	s_waitcnt lgkmcnt(9)
	v_mfma_f32_16x16x32_bf16 v[46:49], v[172:175], v[58:61], v[46:49]
	ds_read_b128 v[164:167], v94 offset:6592
	ds_read_b128 v[168:171], v127 offset:16128
	ds_read_b128 v[172:175], v127 offset:16192
	s_waitcnt lgkmcnt(11)
	v_pk_mul_f32 v[30:31], v[30:31], v[128:129]
	v_pk_mul_f32 v[32:33], v[32:33], v[130:131]
	s_waitcnt lgkmcnt(10)
	s_nop 0
	v_mfma_f32_16x16x32_bf16 v[30:33], v[132:135], v[62:65], v[30:33]
	s_waitcnt lgkmcnt(9)
	v_mfma_f32_16x16x32_bf16 v[30:33], v[136:139], v[58:61], v[30:33]
	s_waitcnt lgkmcnt(8)
	v_pk_mul_f32 v[38:39], v[38:39], v[140:141]
	v_pk_mul_f32 v[40:41], v[40:41], v[142:143]
	s_waitcnt lgkmcnt(7)
	s_nop 0
	v_mfma_f32_16x16x32_bf16 v[38:41], v[144:147], v[62:65], v[38:41]
	s_waitcnt lgkmcnt(6)
	v_mfma_f32_16x16x32_bf16 v[38:41], v[148:151], v[58:61], v[38:41]
	s_waitcnt lgkmcnt(5)
	v_pk_mul_f32 v[26:27], v[26:27], v[152:153]
	v_pk_mul_f32 v[28:29], v[28:29], v[154:155]
	s_waitcnt lgkmcnt(4)
	s_nop 0
	v_mfma_f32_16x16x32_bf16 v[26:29], v[156:159], v[62:65], v[26:29]
	s_waitcnt lgkmcnt(3)
	v_mfma_f32_16x16x32_bf16 v[26:29], v[160:163], v[58:61], v[26:29]
	s_waitcnt lgkmcnt(2)
	v_pk_mul_f32 v[34:35], v[34:35], v[164:165]
	v_pk_mul_f32 v[36:37], v[36:37], v[166:167]
	s_waitcnt lgkmcnt(1)
	s_nop 0
	v_mfma_f32_16x16x32_bf16 v[34:37], v[168:171], v[62:65], v[34:37]
	s_waitcnt lgkmcnt(0)
	s_barrier
	v_mfma_f32_16x16x32_bf16 v[34:37], v[172:175], v[58:61], v[34:37]
	s_cbranch_scc1 .LBB0_1472

.LBB0_1444:
	v_pk_add_f32 v[76:77], v[64:65], v[76:77] neg_lo:[0,1] neg_hi:[0,1]
	v_mul_u32_u24_e32 v0, s73, v0
	v_mul_f32_e32 v76, 0x3fb8aa3b, v76
	v_mul_f32_e32 v77, 0x3fb8aa3b, v77
	v_exp_f32_e32 v76, v76
	v_exp_f32_e32 v77, v77
	s_mov_b32 s2, 0xffff
	s_andn2_b64 vcc, exec, s[54:55]
	v_mul_f32_e32 v70, v76, v70
	v_mul_f32_e32 v60, v76, v60
	v_mul_f32_e32 v78, v77, v61
	v_mul_f32_e32 v58, v76, v58
	v_mul_f32_e32 v80, v77, v59
	v_mul_f32_e32 v59, v76, v79
	v_mul_f32_e32 v61, v76, v74
	v_mul_f32_e32 v72, v76, v72
	v_mul_f32_e32 v68, v76, v68
	v_mul_f32_e32 v69, v77, v69
	v_mul_f32_e32 v66, v76, v66
	v_mul_f32_e32 v67, v77, v67
	v_cvt_pk_bf16_f32 v58, v59, v58
	v_cvt_pk_bf16_f32 v59, v60, v66
	v_cvt_pk_bf16_f32 v60, v68, v70
	v_cvt_pk_bf16_f32 v61, v72, v61
	v_add_u32_e32 v70, s84, v0
	v_mul_f32_e32 v73, v77, v73
	v_mul_f32_e32 v71, v77, v71
	v_mul_f32_e32 v79, v77, v81
	v_mul_f32_e32 v74, v77, v75
	v_cvt_pk_bf16_f32 v66, v79, v80
	v_cvt_pk_bf16_f32 v67, v78, v67
	v_cvt_pk_bf16_f32 v68, v69, v71
	v_cvt_pk_bf16_f32 v69, v73, v74
	ds_write_b128 v70, v[58:61]
	ds_write_b128 v70, v[66:69] offset:144
	v_lshlrev_b32_e32 v58, 16, v3
	v_lshlrev_b32_e32 v59, 16, v5
	v_lshlrev_b32_e32 v60, 16, v7
	s_waitcnt vmcnt(8)
	v_lshlrev_b32_e32 v61, 16, v25
	v_and_or_b32 v58, v2, s2, v58
	v_and_or_b32 v59, v4, s2, v59
	v_and_or_b32 v60, v6, s2, v60
	v_and_or_b32 v61, v24, s2, v61
	v_lshrrev_b32_e32 v66, 16, v2
	s_mov_b32 s2, 0xffff0000
	v_lshrrev_b32_e32 v67, 16, v4
	v_lshrrev_b32_e32 v68, 16, v6
	v_lshrrev_b32_e32 v69, 16, v24
	v_and_or_b32 v66, v3, s2, v66
	v_and_or_b32 v67, v5, s2, v67
	v_and_or_b32 v68, v7, s2, v68
	v_and_or_b32 v69, v25, s2, v69
	v_add_u32_e32 v0, s85, v0
	ds_write_b128 v0, v[58:61]
	ds_write_b128 v0, v[66:69] offset:144
	s_cbranch_vccnz .LBB0_1446
	v_mul_f32_e32 v0, 0x3fb8aa3b, v64
	v_exp_f32_e32 v58, v0
	v_mul_f32_e32 v0, 0x3fb8aa3b, v65
	v_exp_f32_e32 v59, v0
	ds_write_b64 v111, v[58:59] offset:6144
.LBB0_1446:
	s_waitcnt lgkmcnt(0)
	s_barrier
	s_andn2_b64 vcc, exec, s[64:65]
	s_cbranch_vccnz .Lc1_noread
	s_movk_i32 s26, 0x110
	v_readlane_b32 s2, v254, 49
	v_add_u32_e32 v160, s86, v99
	v_lshlrev_b32_e32 v161, 4, v100
	v_mad_u32_u24 v162, v160, s26, v161
	v_add_u32_e32 v160, s88, v99
	v_add_u32_e32 v160, s2, v160
	v_mad_u32_u24 v163, v160, s26, v161


	ds_read_b128 v[128:131], v162 offset:8192
	ds_read_b128 v[132:135], v163 offset:43008
	ds_read_b128 v[136:139], v162 offset:8256
	ds_read_b128 v[140:143], v163 offset:43072
	ds_read_b128 v[144:147], v162 offset:8320
	ds_read_b128 v[148:151], v163 offset:43136
	ds_read_b128 v[152:155], v162 offset:8384
	ds_read_b128 v[156:159], v163 offset:43200

.LBB0_1469:
	s_andn2_b64 vcc, exec, s[70:71]
	s_cbranch_vccnz .Lc2_noread
	s_movk_i32 s26, 0x110
	v_readlane_b32 s2, v254, 53
	v_add_u32_e32 v160, s82, v99
	v_mad_u32_u24 v162, v160, s26, v0
	v_add_u32_e32 v160, s2, v68
	v_mad_u32_u24 v163, v160, s26, v0


	ds_read_b128 v[128:131], v162 offset:8192
	ds_read_b128 v[132:135], v163 offset:43008
	ds_read_b128 v[136:139], v162 offset:8256
	ds_read_b128 v[140:143], v163 offset:43072
	ds_read_b128 v[144:147], v162 offset:8320
	ds_read_b128 v[148:151], v163 offset:43136
	ds_read_b128 v[152:155], v162 offset:8384
	ds_read_b128 v[156:159], v163 offset:43200
.Lc2_noread:
	v_lshl_add_u32 v66, v99, 1, s77
	v_add_u32_e32 v59, s86, v67
	s_movk_i32 s26, 0x7fff
	v_mad_u32_u24 v70, v59, s73, v66
	s_nop 2
	v_bfe_u32 v59, v61, 16, 1
	v_add3_u32 v59, v61, v59, s26
	ds_write_b16_d16_hi v70, v59 offset:144
	v_bfe_u32 v59, v62, 16, 1
	v_add3_u32 v59, v62, v59, s26
	v_bfe_u32 v69, v60, 16, 1
	ds_write_b16_d16_hi v70, v59 offset:288
	v_bfe_u32 v59, v63, 16, 1
	v_add3_u32 v60, v60, v69, s26
	v_add3_u32 v59, v63, v59, s26
	ds_write_b16_d16_hi v70, v60
	ds_write_b16_d16_hi v70, v59 offset:432
	s_andn2_b64 vcc, exec, s[70:71]
	v_mov_b32_e32 v59, 0
	v_mov_b32_e32 v60, 0
	v_mov_b32_e32 v61, 0
	s_cbranch_vccnz .LBB0_1409
	v_readlane_b32 s2, v254, 54
	v_readlane_b32 s3, v254, 55
	s_waitcnt lgkmcnt(10)
	v_mfma_f32_16x16x32_bf16 v[58:61], v[128:131], v[132:135], 0
	s_andn2_b64 vcc, exec, s[2:3]
	s_waitcnt lgkmcnt(8)
	v_mfma_f32_16x16x32_bf16 v[58:61], v[136:139], v[140:143], v[58:61]
	s_waitcnt lgkmcnt(6)
	v_mfma_f32_16x16x32_bf16 v[58:61], v[144:147], v[148:151], v[58:61]
	s_waitcnt lgkmcnt(4)
	v_mfma_f32_16x16x32_bf16 v[58:61], v[152:155], v[156:159], v[58:61]
	s_cbranch_vccnz .LBB0_1409
	v_cmp_le_i32_e32 vcc, v99, v67
	v_or_b32_e32 v0, 1, v67
	s_nop 4
	v_cndmask_b32_e32 v58, 0, v58, vcc
	v_cmp_le_i32_e32 vcc, v99, v0
	v_or_b32_e32 v0, 2, v67
	s_nop 0
	v_cndmask_b32_e32 v59, 0, v59, vcc
	v_cmp_le_i32_e32 vcc, v99, v0
	v_or_b32_e32 v0, 3, v67
	s_nop 0
	v_cndmask_b32_e32 v60, 0, v60, vcc
	v_cmp_le_i32_e32 vcc, v99, v0
	s_nop 1
	v_cndmask_b32_e32 v61, 0, v61, vcc
	s_branch .LBB0_1409
